# in-proj/ffn1: first k-iteration after an epilogue waits vmcnt(40) instead of vmcnt(8) in its first two load segments (the tile stores may stay in flight; fragments were staged before them)
# baseline (speedup 1.0000x reference)
.LBB0_10:
	s_mov_b32 s101, 0
	s_cmp_lg_u32 s92, 0
	s_mov_b64 s[0:1], -1
	s_cbranch_scc1 .LBB0_11
	s_getpc_b64 s[98:99]

.LBB0_37:
	s_add_u32 s4, s54, 0xfffc0080
	s_addc_u32 s5, s55, -1
	s_add_i32 s61, 0, 0x10000
	s_cmp_eq_u32 s60, 12
	s_cselect_b32 s57, s29, s5
	s_cselect_b32 s56, s33, s4
	v_add_u32_e32 v138, s61, v150
	s_cselect_b32 s5, s47, s59
	s_cselect_b32 s4, s49, s58
	s_add_i32 s64, 0, 0x14000
	ds_read_b128 v[152:155], v138
	ds_read_b128 v[156:159], v138 offset:1024
	ds_read_b128 v[160:163], v138 offset:2048
	ds_read_b128 v[164:167], v138 offset:3072
	v_add_u32_e32 v138, s64, v150
	ds_read_b128 v[168:171], v138
	ds_read_b128 v[172:175], v138 offset:1024
	ds_read_b128 v[184:187], v138 offset:2048
	ds_read_b128 v[188:191], v138 offset:3072
	v_lshl_add_u64 v[138:139], s[54:55], 0, v[142:143]
	s_add_i32 m0, s3, 0xc000
	ds_read_b128 v[192:195], v151
	ds_read_b128 v[196:199], v151 offset:1024
	ds_read_b128 v[200:203], v151 offset:2048
	ds_read_b128 v[204:207], v151 offset:3072
	ds_read_b128 v[208:211], v151 offset:4096
	ds_read_b128 v[212:215], v151 offset:5120
	ds_read_b128 v[216:219], v151 offset:6144
	ds_read_b128 v[220:223], v151 offset:7168
	global_load_lds_dwordx4 v[138:139], off
	v_lshl_add_u64 v[138:139], s[54:55], 0, v[144:145]
	s_add_i32 m0, s3, 0xe000
	s_nop 0
	global_load_lds_dwordx4 v[138:139], off
	s_cmp_eq_u32 s101, 1
	s_cbranch_scc1 .Lrlx_lbb0_37_0
	s_waitcnt vmcnt(8)
.Lrlx_lbb0_37_0:
	s_waitcnt vmcnt(40)
	s_waitcnt lgkmcnt(0)
	s_barrier
	s_setprio 1
	s_waitcnt lgkmcnt(0)
	v_mfma_f32_16x16x32_bf16 v[126:129], v[152:155], v[192:195], v[126:129]
	v_mfma_f32_16x16x32_bf16 v[122:125], v[160:163], v[192:195], v[122:125]
	v_mfma_f32_16x16x32_bf16 v[110:113], v[152:155], v[200:203], v[110:113]
	v_mfma_f32_16x16x32_bf16 v[106:109], v[160:163], v[200:203], v[106:109]
	v_mfma_f32_16x16x32_bf16 v[94:97], v[152:155], v[208:211], v[94:97]
	v_mfma_f32_16x16x32_bf16 v[90:93], v[160:163], v[208:211], v[90:93]
	v_mfma_f32_16x16x32_bf16 v[78:81], v[152:155], v[216:219], v[78:81]
	v_mfma_f32_16x16x32_bf16 v[74:77], v[160:163], v[216:219], v[74:77]
	v_mfma_f32_16x16x32_bf16 v[126:129], v[156:159], v[196:199], v[126:129]
	v_mfma_f32_16x16x32_bf16 v[122:125], v[164:167], v[196:199], v[122:125]
	v_mfma_f32_16x16x32_bf16 v[110:113], v[156:159], v[204:207], v[110:113]
	v_mfma_f32_16x16x32_bf16 v[106:109], v[164:167], v[204:207], v[106:109]
	v_mfma_f32_16x16x32_bf16 v[94:97], v[156:159], v[212:215], v[94:97]
	v_mfma_f32_16x16x32_bf16 v[90:93], v[164:167], v[212:215], v[90:93]
	v_mfma_f32_16x16x32_bf16 v[78:81], v[156:159], v[220:223], v[78:81]
	v_mfma_f32_16x16x32_bf16 v[74:77], v[164:167], v[220:223], v[74:77]
	s_setprio 0
	s_setprio 1
	v_mfma_f32_16x16x32_bf16 v[118:121], v[168:171], v[192:195], v[118:121]
	v_mfma_f32_16x16x32_bf16 v[114:117], v[184:187], v[192:195], v[114:117]
	v_mfma_f32_16x16x32_bf16 v[102:105], v[168:171], v[200:203], v[102:105]
	v_mfma_f32_16x16x32_bf16 v[98:101], v[184:187], v[200:203], v[98:101]
	v_mfma_f32_16x16x32_bf16 v[86:89], v[168:171], v[208:211], v[86:89]
	v_mfma_f32_16x16x32_bf16 v[82:85], v[184:187], v[208:211], v[82:85]
	v_mfma_f32_16x16x32_bf16 v[70:73], v[168:171], v[216:219], v[70:73]
	v_mfma_f32_16x16x32_bf16 v[66:69], v[184:187], v[216:219], v[66:69]
	v_mfma_f32_16x16x32_bf16 v[118:121], v[172:175], v[196:199], v[118:121]
	v_mfma_f32_16x16x32_bf16 v[114:117], v[188:191], v[196:199], v[114:117]
	v_mfma_f32_16x16x32_bf16 v[102:105], v[172:175], v[204:207], v[102:105]
	v_mfma_f32_16x16x32_bf16 v[98:101], v[188:191], v[204:207], v[98:101]
	v_mfma_f32_16x16x32_bf16 v[86:89], v[172:175], v[212:215], v[86:89]
	v_mfma_f32_16x16x32_bf16 v[82:85], v[188:191], v[212:215], v[82:85]
	v_mfma_f32_16x16x32_bf16 v[70:73], v[172:175], v[220:223], v[70:73]
	v_mfma_f32_16x16x32_bf16 v[66:69], v[188:191], v[220:223], v[66:69]
	s_setprio 0
	s_barrier
	s_add_i32 s61, s61, s2
	v_lshl_add_u64 v[138:139], s[4:5], 0, v[134:135]
	s_mov_b32 m0, s61
	ds_read_b128 v[192:195], v151 offset:16384
	ds_read_b128 v[196:199], v151 offset:17408
	ds_read_b128 v[200:203], v151 offset:18432
	ds_read_b128 v[204:207], v151 offset:19456
	ds_read_b128 v[208:211], v151 offset:20480
	ds_read_b128 v[212:215], v151 offset:21504
	ds_read_b128 v[216:219], v151 offset:22528
	ds_read_b128 v[220:223], v151 offset:23552
	global_load_lds_dwordx4 v[138:139], off
	s_add_i32 m0, s61, 0x2000
	s_add_u32 s62, s4, 0x40000
	v_lshl_add_u64 v[148:149], s[4:5], 0, v[130:131]
	s_addc_u32 s63, s5, 0
	s_add_i32 s61, s64, s2
	global_load_lds_dwordx4 v[148:149], off
	v_lshl_add_u64 v[182:183], s[62:63], 0, v[134:135]
	s_mov_b32 m0, s61
	v_lshl_add_u64 v[224:225], s[56:57], 0, v[132:133]
	global_load_lds_dwordx4 v[182:183], off
	v_lshl_add_u64 v[182:183], s[62:63], 0, v[130:131]
	s_add_i32 m0, s61, 0x2000
	s_nop 0
	global_load_lds_dwordx4 v[182:183], off
	v_lshl_add_u64 v[182:183], s[56:57], 0, v[136:137]
	s_mov_b32 m0, s3
	s_nop 0
	global_load_lds_dwordx4 v[182:183], off
	s_mov_b32 m0, s10
	s_nop 0
	global_load_lds_dwordx4 v[224:225], off
	s_cmp_eq_u32 s101, 1
	s_cbranch_scc1 .Lrlx_lbb0_37_1
	s_waitcnt vmcnt(8)
.Lrlx_lbb0_37_1:
	s_waitcnt vmcnt(40)
	s_mov_b32 s101, 0
	s_waitcnt lgkmcnt(0)
	s_barrier
	s_setprio 1
	s_waitcnt lgkmcnt(0)
	v_mfma_f32_16x16x32_bf16 v[60:63], v[152:155], v[192:195], v[60:63]
	v_mfma_f32_16x16x32_bf16 v[56:59], v[160:163], v[192:195], v[56:59]
	v_mfma_f32_16x16x32_bf16 v[44:47], v[152:155], v[200:203], v[44:47]
	v_mfma_f32_16x16x32_bf16 v[40:43], v[160:163], v[200:203], v[40:43]
	v_mfma_f32_16x16x32_bf16 v[28:31], v[152:155], v[208:211], v[28:31]
	v_mfma_f32_16x16x32_bf16 v[24:27], v[160:163], v[208:211], v[24:27]
	v_mfma_f32_16x16x32_bf16 v[12:15], v[152:155], v[216:219], v[12:15]
	v_mfma_f32_16x16x32_bf16 v[8:11], v[160:163], v[216:219], v[8:11]
	v_mfma_f32_16x16x32_bf16 v[60:63], v[156:159], v[196:199], v[60:63]
	v_mfma_f32_16x16x32_bf16 v[56:59], v[164:167], v[196:199], v[56:59]
	v_mfma_f32_16x16x32_bf16 v[44:47], v[156:159], v[204:207], v[44:47]
	v_mfma_f32_16x16x32_bf16 v[40:43], v[164:167], v[204:207], v[40:43]
	v_mfma_f32_16x16x32_bf16 v[28:31], v[156:159], v[212:215], v[28:31]
	v_mfma_f32_16x16x32_bf16 v[24:27], v[164:167], v[212:215], v[24:27]
	v_mfma_f32_16x16x32_bf16 v[12:15], v[156:159], v[220:223], v[12:15]
	v_mfma_f32_16x16x32_bf16 v[8:11], v[164:167], v[220:223], v[8:11]
	s_setprio 0
	s_setprio 1
	v_mfma_f32_16x16x32_bf16 v[52:55], v[168:171], v[192:195], v[52:55]
	v_mfma_f32_16x16x32_bf16 v[48:51], v[184:187], v[192:195], v[48:51]
	v_mfma_f32_16x16x32_bf16 v[36:39], v[168:171], v[200:203], v[36:39]
	v_mfma_f32_16x16x32_bf16 v[32:35], v[184:187], v[200:203], v[32:35]
	v_mfma_f32_16x16x32_bf16 v[20:23], v[168:171], v[208:211], v[20:23]
	v_mfma_f32_16x16x32_bf16 v[16:19], v[184:187], v[208:211], v[16:19]
	v_mfma_f32_16x16x32_bf16 v[4:7], v[168:171], v[216:219], v[4:7]
	v_mfma_f32_16x16x32_bf16 v[0:3], v[184:187], v[216:219], v[0:3]
	v_mfma_f32_16x16x32_bf16 v[52:55], v[172:175], v[196:199], v[52:55]
	v_mfma_f32_16x16x32_bf16 v[48:51], v[188:191], v[196:199], v[48:51]
	v_mfma_f32_16x16x32_bf16 v[36:39], v[172:175], v[204:207], v[36:39]
	v_mfma_f32_16x16x32_bf16 v[32:35], v[188:191], v[204:207], v[32:35]
	v_mfma_f32_16x16x32_bf16 v[20:23], v[172:175], v[212:215], v[20:23]
	v_mfma_f32_16x16x32_bf16 v[16:19], v[188:191], v[212:215], v[16:19]
	v_mfma_f32_16x16x32_bf16 v[4:7], v[172:175], v[220:223], v[4:7]
	v_mfma_f32_16x16x32_bf16 v[0:3], v[188:191], v[220:223], v[0:3]
	s_setprio 0
	s_barrier
	s_add_i32 s61, 0, 0x18000
	v_add_u32_e32 v147, s61, v150
	s_add_i32 s62, 0, 0x1c000
	ds_read_b128 v[152:155], v147
	ds_read_b128 v[156:159], v147 offset:1024
	ds_read_b128 v[160:163], v147 offset:2048
	ds_read_b128 v[164:167], v147 offset:3072
	v_add_u32_e32 v147, s62, v150
	ds_read_b128 v[168:171], v147
	ds_read_b128 v[172:175], v147 offset:1024
	ds_read_b128 v[184:187], v147 offset:2048
	ds_read_b128 v[188:191], v147 offset:3072
	s_add_u32 s56, s56, 0x40000
	s_addc_u32 s57, s57, 0
	s_mov_b32 m0, s18
	v_lshl_add_u64 v[226:227], s[56:57], 0, v[136:137]
	ds_read_b128 v[192:195], v151 offset:32768
	ds_read_b128 v[196:199], v151 offset:33792
	ds_read_b128 v[200:203], v151 offset:34816
	ds_read_b128 v[204:207], v151 offset:35840
	ds_read_b128 v[208:211], v151 offset:36864
	ds_read_b128 v[212:215], v151 offset:37888
	ds_read_b128 v[216:219], v151 offset:38912
	ds_read_b128 v[220:223], v151 offset:39936
	global_load_lds_dwordx4 v[226:227], off
	v_lshl_add_u64 v[226:227], s[56:57], 0, v[132:133]
	s_mov_b32 m0, s19
	s_nop 0
	global_load_lds_dwordx4 v[226:227], off
	s_waitcnt vmcnt(8)
	s_waitcnt lgkmcnt(0)
	s_barrier
	s_setprio 1
	s_waitcnt lgkmcnt(0)
	v_mfma_f32_16x16x32_bf16 v[126:129], v[152:155], v[192:195], v[126:129]
	v_mfma_f32_16x16x32_bf16 v[122:125], v[160:163], v[192:195], v[122:125]
	v_mfma_f32_16x16x32_bf16 v[110:113], v[152:155], v[200:203], v[110:113]
	v_mfma_f32_16x16x32_bf16 v[106:109], v[160:163], v[200:203], v[106:109]
	v_mfma_f32_16x16x32_bf16 v[94:97], v[152:155], v[208:211], v[94:97]
	v_mfma_f32_16x16x32_bf16 v[90:93], v[160:163], v[208:211], v[90:93]
	v_mfma_f32_16x16x32_bf16 v[78:81], v[152:155], v[216:219], v[78:81]
	v_mfma_f32_16x16x32_bf16 v[74:77], v[160:163], v[216:219], v[74:77]
	v_mfma_f32_16x16x32_bf16 v[126:129], v[156:159], v[196:199], v[126:129]
	v_mfma_f32_16x16x32_bf16 v[122:125], v[164:167], v[196:199], v[122:125]
	v_mfma_f32_16x16x32_bf16 v[110:113], v[156:159], v[204:207], v[110:113]
	v_mfma_f32_16x16x32_bf16 v[106:109], v[164:167], v[204:207], v[106:109]
	v_mfma_f32_16x16x32_bf16 v[94:97], v[156:159], v[212:215], v[94:97]
	v_mfma_f32_16x16x32_bf16 v[90:93], v[164:167], v[212:215], v[90:93]
	v_mfma_f32_16x16x32_bf16 v[78:81], v[156:159], v[220:223], v[78:81]
	v_mfma_f32_16x16x32_bf16 v[74:77], v[164:167], v[220:223], v[74:77]
	s_setprio 0
	s_setprio 1
	v_mfma_f32_16x16x32_bf16 v[118:121], v[168:171], v[192:195], v[118:121]
	v_mfma_f32_16x16x32_bf16 v[114:117], v[184:187], v[192:195], v[114:117]
	v_mfma_f32_16x16x32_bf16 v[102:105], v[168:171], v[200:203], v[102:105]
	v_mfma_f32_16x16x32_bf16 v[98:101], v[184:187], v[200:203], v[98:101]
	v_mfma_f32_16x16x32_bf16 v[86:89], v[168:171], v[208:211], v[86:89]
	v_mfma_f32_16x16x32_bf16 v[82:85], v[184:187], v[208:211], v[82:85]
	v_mfma_f32_16x16x32_bf16 v[70:73], v[168:171], v[216:219], v[70:73]
	v_mfma_f32_16x16x32_bf16 v[66:69], v[184:187], v[216:219], v[66:69]
	v_mfma_f32_16x16x32_bf16 v[118:121], v[172:175], v[196:199], v[118:121]
	v_mfma_f32_16x16x32_bf16 v[114:117], v[188:191], v[196:199], v[114:117]
	v_mfma_f32_16x16x32_bf16 v[102:105], v[172:175], v[204:207], v[102:105]
	v_mfma_f32_16x16x32_bf16 v[98:101], v[188:191], v[204:207], v[98:101]
	v_mfma_f32_16x16x32_bf16 v[86:89], v[172:175], v[212:215], v[86:89]
	v_mfma_f32_16x16x32_bf16 v[82:85], v[188:191], v[212:215], v[82:85]
	v_mfma_f32_16x16x32_bf16 v[70:73], v[172:175], v[220:223], v[70:73]
	v_mfma_f32_16x16x32_bf16 v[66:69], v[188:191], v[220:223], v[66:69]
	s_setprio 0
	s_barrier
	s_add_i32 s56, s61, s2
	v_lshl_add_u64 v[138:139], v[138:139], 0, s[14:15]
	s_mov_b32 m0, s56
	ds_read_b128 v[192:195], v151 offset:49152
	ds_read_b128 v[196:199], v151 offset:50176
	ds_read_b128 v[200:203], v151 offset:51200
	ds_read_b128 v[204:207], v151 offset:52224
	ds_read_b128 v[208:211], v151 offset:53248
	ds_read_b128 v[212:215], v151 offset:54272
	ds_read_b128 v[216:219], v151 offset:55296
	ds_read_b128 v[220:223], v151 offset:56320
	global_load_lds_dwordx4 v[138:139], off
	s_add_i32 m0, s56, 0x2000
	s_add_u32 s4, s4, 0x40080
	v_lshl_add_u64 v[138:139], v[148:149], 0, s[14:15]
	s_addc_u32 s5, s5, 0
	s_add_i32 s56, s62, s2
	global_load_lds_dwordx4 v[138:139], off
	v_lshl_add_u64 v[138:139], s[4:5], 0, v[134:135]
	s_mov_b32 m0, s56
	s_nop 0
	global_load_lds_dwordx4 v[138:139], off
	v_lshl_add_u64 v[138:139], s[4:5], 0, v[130:131]
	s_add_i32 m0, s56, 0x2000
	s_nop 0
	global_load_lds_dwordx4 v[138:139], off
	v_lshl_add_u64 v[138:139], v[182:183], 0, s[14:15]
	s_mov_b32 m0, s20
	s_nop 0
	global_load_lds_dwordx4 v[138:139], off
	v_lshl_add_u64 v[138:139], v[224:225], 0, s[14:15]
	s_mov_b32 m0, s21
	s_nop 0
	global_load_lds_dwordx4 v[138:139], off
	s_waitcnt vmcnt(8)
	s_waitcnt lgkmcnt(0)
	s_barrier
	s_setprio 1
	s_waitcnt lgkmcnt(0)
	v_mfma_f32_16x16x32_bf16 v[60:63], v[152:155], v[192:195], v[60:63]
	v_mfma_f32_16x16x32_bf16 v[56:59], v[160:163], v[192:195], v[56:59]
	v_mfma_f32_16x16x32_bf16 v[44:47], v[152:155], v[200:203], v[44:47]
	v_mfma_f32_16x16x32_bf16 v[40:43], v[160:163], v[200:203], v[40:43]
	v_mfma_f32_16x16x32_bf16 v[28:31], v[152:155], v[208:211], v[28:31]
	v_mfma_f32_16x16x32_bf16 v[24:27], v[160:163], v[208:211], v[24:27]
	v_mfma_f32_16x16x32_bf16 v[12:15], v[152:155], v[216:219], v[12:15]
	v_mfma_f32_16x16x32_bf16 v[8:11], v[160:163], v[216:219], v[8:11]
	v_mfma_f32_16x16x32_bf16 v[60:63], v[156:159], v[196:199], v[60:63]
	v_mfma_f32_16x16x32_bf16 v[56:59], v[164:167], v[196:199], v[56:59]
	v_mfma_f32_16x16x32_bf16 v[44:47], v[156:159], v[204:207], v[44:47]
	v_mfma_f32_16x16x32_bf16 v[40:43], v[164:167], v[204:207], v[40:43]
	v_mfma_f32_16x16x32_bf16 v[28:31], v[156:159], v[212:215], v[28:31]
	v_mfma_f32_16x16x32_bf16 v[24:27], v[164:167], v[212:215], v[24:27]
	v_mfma_f32_16x16x32_bf16 v[12:15], v[156:159], v[220:223], v[12:15]
	v_mfma_f32_16x16x32_bf16 v[8:11], v[164:167], v[220:223], v[8:11]
	s_setprio 0
	s_setprio 1
	v_mfma_f32_16x16x32_bf16 v[52:55], v[168:171], v[192:195], v[52:55]
	v_mfma_f32_16x16x32_bf16 v[48:51], v[184:187], v[192:195], v[48:51]
	v_mfma_f32_16x16x32_bf16 v[36:39], v[168:171], v[200:203], v[36:39]
	v_mfma_f32_16x16x32_bf16 v[32:35], v[184:187], v[200:203], v[32:35]
	v_mfma_f32_16x16x32_bf16 v[20:23], v[168:171], v[208:211], v[20:23]
	v_mfma_f32_16x16x32_bf16 v[16:19], v[184:187], v[208:211], v[16:19]
	v_mfma_f32_16x16x32_bf16 v[4:7], v[168:171], v[216:219], v[4:7]
	v_mfma_f32_16x16x32_bf16 v[0:3], v[184:187], v[216:219], v[0:3]
	v_mfma_f32_16x16x32_bf16 v[52:55], v[172:175], v[196:199], v[52:55]
	v_mfma_f32_16x16x32_bf16 v[48:51], v[188:191], v[196:199], v[48:51]
	v_mfma_f32_16x16x32_bf16 v[36:39], v[172:175], v[204:207], v[36:39]
	v_mfma_f32_16x16x32_bf16 v[32:35], v[188:191], v[204:207], v[32:35]
	v_mfma_f32_16x16x32_bf16 v[20:23], v[172:175], v[212:215], v[20:23]
	v_mfma_f32_16x16x32_bf16 v[16:19], v[188:191], v[212:215], v[16:19]
	v_mfma_f32_16x16x32_bf16 v[4:7], v[172:175], v[220:223], v[4:7]
	v_mfma_f32_16x16x32_bf16 v[0:3], v[188:191], v[220:223], v[0:3]
	s_setprio 0
	s_barrier
	s_add_i32 s60, s60, 2
	s_add_u32 s54, s54, 0x100
	s_addc_u32 s55, s55, 0
	s_add_u32 s58, s58, 0x100
	s_addc_u32 s59, s59, 0
	s_cmp_gt_u32 s60, 13
	s_cbranch_scc0 .LBB0_37
	s_and_b64 vcc, exec, s[40:41]
	s_cbranch_vccz .LBB0_40
	s_barrier

.Lffn1_done:
	s_mov_b32 s101, 1
	s_cbranch_vccnz .LBB0_29
	s_andn2_b64 vcc, exec, s[36:37]
	s_cbranch_vccnz .LBB0_28
	s_barrier
	s_branch .LBB0_28

.LBB0_581:
	s_add_u32 s4, s0, 0xfffc0080
	s_addc_u32 s5, s1, -1
	s_add_i32 s24, 0, 0x10000
	s_cmp_eq_u32 s21, 12
	s_cselect_b32 s37, s8, s5
	s_cselect_b32 s36, s9, s4
	v_add_u32_e32 v138, s24, v191
	s_cselect_b32 s5, s10, s20
	s_cselect_b32 s4, s18, s19
	s_add_i32 s28, 0, 0x14000
	ds_read_b128 v[130:133], v138
	ds_read_b128 v[134:137], v138 offset:1024
	ds_read_b128 v[158:161], v138 offset:2048
	ds_read_b128 v[162:165], v138 offset:3072
	v_add_u32_e32 v138, s28, v191
	ds_read_b128 v[196:199], v138
	ds_read_b128 v[200:203], v138 offset:1024
	ds_read_b128 v[204:207], v138 offset:2048
	ds_read_b128 v[208:211], v138 offset:3072
	v_lshl_add_u64 v[166:167], s[0:1], 0, v[152:153]
	s_add_i32 m0, s61, 0xc000
	ds_read_b128 v[212:215], v194
	ds_read_b128 v[216:219], v194 offset:1024
	ds_read_b128 v[220:223], v194 offset:2048
	ds_read_b128 v[224:227], v194 offset:3072
	ds_read_b128 v[228:231], v194 offset:4096
	ds_read_b128 v[232:235], v194 offset:5120
	ds_read_b128 v[236:239], v194 offset:6144
	ds_read_b128 v[240:243], v194 offset:7168
	global_load_lds_dwordx4 v[166:167], off
	v_lshl_add_u64 v[166:167], s[0:1], 0, v[154:155]
	s_add_i32 m0, s61, 0xe000
	s_nop 0
	global_load_lds_dwordx4 v[166:167], off
	s_cmp_eq_u32 s101, 1
	s_cbranch_scc1 .Lrlx_lbb0_581_0
	s_waitcnt vmcnt(8)
.Lrlx_lbb0_581_0:
	s_waitcnt vmcnt(40)
	s_waitcnt lgkmcnt(0)
	s_barrier
	s_setprio 1
	s_waitcnt lgkmcnt(0)
	v_mfma_f32_16x16x32_bf16 v[126:129], v[130:133], v[212:215], v[126:129]
	v_mfma_f32_16x16x32_bf16 v[122:125], v[158:161], v[212:215], v[122:125]
	v_mfma_f32_16x16x32_bf16 v[110:113], v[130:133], v[220:223], v[110:113]
	v_mfma_f32_16x16x32_bf16 v[106:109], v[158:161], v[220:223], v[106:109]
	v_mfma_f32_16x16x32_bf16 v[94:97], v[130:133], v[228:231], v[94:97]
	v_mfma_f32_16x16x32_bf16 v[90:93], v[158:161], v[228:231], v[90:93]
	v_mfma_f32_16x16x32_bf16 v[78:81], v[130:133], v[236:239], v[78:81]
	v_mfma_f32_16x16x32_bf16 v[74:77], v[158:161], v[236:239], v[74:77]
	v_mfma_f32_16x16x32_bf16 v[126:129], v[134:137], v[216:219], v[126:129]
	v_mfma_f32_16x16x32_bf16 v[122:125], v[162:165], v[216:219], v[122:125]
	v_mfma_f32_16x16x32_bf16 v[110:113], v[134:137], v[224:227], v[110:113]
	v_mfma_f32_16x16x32_bf16 v[106:109], v[162:165], v[224:227], v[106:109]
	v_mfma_f32_16x16x32_bf16 v[94:97], v[134:137], v[232:235], v[94:97]
	v_mfma_f32_16x16x32_bf16 v[90:93], v[162:165], v[232:235], v[90:93]
	v_mfma_f32_16x16x32_bf16 v[78:81], v[134:137], v[240:243], v[78:81]
	v_mfma_f32_16x16x32_bf16 v[74:77], v[162:165], v[240:243], v[74:77]
	s_setprio 0
	s_setprio 1
	v_mfma_f32_16x16x32_bf16 v[118:121], v[196:199], v[212:215], v[118:121]
	v_mfma_f32_16x16x32_bf16 v[114:117], v[204:207], v[212:215], v[114:117]
	v_mfma_f32_16x16x32_bf16 v[102:105], v[196:199], v[220:223], v[102:105]
	v_mfma_f32_16x16x32_bf16 v[98:101], v[204:207], v[220:223], v[98:101]
	v_mfma_f32_16x16x32_bf16 v[86:89], v[196:199], v[228:231], v[86:89]
	v_mfma_f32_16x16x32_bf16 v[82:85], v[204:207], v[228:231], v[82:85]
	v_mfma_f32_16x16x32_bf16 v[70:73], v[196:199], v[236:239], v[70:73]
	v_mfma_f32_16x16x32_bf16 v[66:69], v[204:207], v[236:239], v[66:69]
	v_mfma_f32_16x16x32_bf16 v[118:121], v[200:203], v[216:219], v[118:121]
	v_mfma_f32_16x16x32_bf16 v[114:117], v[208:211], v[216:219], v[114:117]
	v_mfma_f32_16x16x32_bf16 v[102:105], v[200:203], v[224:227], v[102:105]
	v_mfma_f32_16x16x32_bf16 v[98:101], v[208:211], v[224:227], v[98:101]
	v_mfma_f32_16x16x32_bf16 v[86:89], v[200:203], v[232:235], v[86:89]
	v_mfma_f32_16x16x32_bf16 v[82:85], v[208:211], v[232:235], v[82:85]
	v_mfma_f32_16x16x32_bf16 v[70:73], v[200:203], v[240:243], v[70:73]
	v_mfma_f32_16x16x32_bf16 v[66:69], v[208:211], v[240:243], v[66:69]
	s_setprio 0
	s_barrier
	s_add_i32 s24, s24, s60
	v_lshl_add_u64 v[166:167], s[4:5], 0, v[146:147]
	s_mov_b32 m0, s24
	ds_read_b128 v[212:215], v194 offset:16384
	ds_read_b128 v[216:219], v194 offset:17408
	ds_read_b128 v[220:223], v194 offset:18432
	ds_read_b128 v[224:227], v194 offset:19456
	ds_read_b128 v[228:231], v194 offset:20480
	ds_read_b128 v[232:235], v194 offset:21504
	ds_read_b128 v[236:239], v194 offset:22528
	ds_read_b128 v[240:243], v194 offset:23552
	global_load_lds_dwordx4 v[166:167], off
	s_add_i32 m0, s24, 0x2000
	s_add_u32 s24, s4, 0x40000
	v_lshl_add_u64 v[244:245], s[4:5], 0, v[142:143]
	s_addc_u32 s25, s5, 0
	s_add_i32 s28, s28, s60
	global_load_lds_dwordx4 v[244:245], off
	v_lshl_add_u64 v[246:247], s[24:25], 0, v[146:147]
	s_mov_b32 m0, s28
	v_lshl_add_u64 v[248:249], s[36:37], 0, v[144:145]
	global_load_lds_dwordx4 v[246:247], off
	v_lshl_add_u64 v[246:247], s[24:25], 0, v[142:143]
	s_add_i32 m0, s28, 0x2000
	s_nop 0
	global_load_lds_dwordx4 v[246:247], off
	v_lshl_add_u64 v[246:247], s[36:37], 0, v[148:149]
	s_mov_b32 m0, s61
	s_nop 0
	global_load_lds_dwordx4 v[246:247], off
	s_mov_b32 m0, s62
	s_nop 0
	global_load_lds_dwordx4 v[248:249], off
	s_cmp_eq_u32 s101, 1
	s_cbranch_scc1 .Lrlx_lbb0_581_1
	s_waitcnt vmcnt(8)
.Lrlx_lbb0_581_1:
	s_waitcnt vmcnt(40)
	s_mov_b32 s101, 0
	s_waitcnt lgkmcnt(0)
	s_barrier
	s_setprio 1
	s_waitcnt lgkmcnt(0)
	v_mfma_f32_16x16x32_bf16 v[60:63], v[130:133], v[212:215], v[60:63]
	v_mfma_f32_16x16x32_bf16 v[56:59], v[158:161], v[212:215], v[56:59]
	v_mfma_f32_16x16x32_bf16 v[44:47], v[130:133], v[220:223], v[44:47]
	v_mfma_f32_16x16x32_bf16 v[40:43], v[158:161], v[220:223], v[40:43]
	v_mfma_f32_16x16x32_bf16 v[28:31], v[130:133], v[228:231], v[28:31]
	v_mfma_f32_16x16x32_bf16 v[24:27], v[158:161], v[228:231], v[24:27]
	v_mfma_f32_16x16x32_bf16 v[12:15], v[130:133], v[236:239], v[12:15]
	v_mfma_f32_16x16x32_bf16 v[8:11], v[158:161], v[236:239], v[8:11]
	v_mfma_f32_16x16x32_bf16 v[60:63], v[134:137], v[216:219], v[60:63]
	v_mfma_f32_16x16x32_bf16 v[56:59], v[162:165], v[216:219], v[56:59]
	v_mfma_f32_16x16x32_bf16 v[44:47], v[134:137], v[224:227], v[44:47]
	v_mfma_f32_16x16x32_bf16 v[40:43], v[162:165], v[224:227], v[40:43]
	v_mfma_f32_16x16x32_bf16 v[28:31], v[134:137], v[232:235], v[28:31]
	v_mfma_f32_16x16x32_bf16 v[24:27], v[162:165], v[232:235], v[24:27]
	v_mfma_f32_16x16x32_bf16 v[12:15], v[134:137], v[240:243], v[12:15]
	v_mfma_f32_16x16x32_bf16 v[8:11], v[162:165], v[240:243], v[8:11]
	s_setprio 0
	s_setprio 1
	v_mfma_f32_16x16x32_bf16 v[52:55], v[196:199], v[212:215], v[52:55]
	v_mfma_f32_16x16x32_bf16 v[48:51], v[204:207], v[212:215], v[48:51]
	v_mfma_f32_16x16x32_bf16 v[36:39], v[196:199], v[220:223], v[36:39]
	v_mfma_f32_16x16x32_bf16 v[32:35], v[204:207], v[220:223], v[32:35]
	v_mfma_f32_16x16x32_bf16 v[20:23], v[196:199], v[228:231], v[20:23]
	v_mfma_f32_16x16x32_bf16 v[16:19], v[204:207], v[228:231], v[16:19]
	v_mfma_f32_16x16x32_bf16 v[4:7], v[196:199], v[236:239], v[4:7]
	v_mfma_f32_16x16x32_bf16 v[0:3], v[204:207], v[236:239], v[0:3]
	v_mfma_f32_16x16x32_bf16 v[52:55], v[200:203], v[216:219], v[52:55]
	v_mfma_f32_16x16x32_bf16 v[48:51], v[208:211], v[216:219], v[48:51]
	v_mfma_f32_16x16x32_bf16 v[36:39], v[200:203], v[224:227], v[36:39]
	v_mfma_f32_16x16x32_bf16 v[32:35], v[208:211], v[224:227], v[32:35]
	v_mfma_f32_16x16x32_bf16 v[20:23], v[200:203], v[232:235], v[20:23]
	v_mfma_f32_16x16x32_bf16 v[16:19], v[208:211], v[232:235], v[16:19]
	v_mfma_f32_16x16x32_bf16 v[4:7], v[200:203], v[240:243], v[4:7]
	v_mfma_f32_16x16x32_bf16 v[0:3], v[208:211], v[240:243], v[0:3]
	s_setprio 0
	s_barrier
	s_add_i32 s28, 0, 0x18000
	v_add_u32_e32 v138, s28, v191
	s_add_i32 s29, 0, 0x1c000
	ds_read_b128 v[130:133], v138
	ds_read_b128 v[134:137], v138 offset:1024
	ds_read_b128 v[158:161], v138 offset:2048
	ds_read_b128 v[162:165], v138 offset:3072
	v_add_u32_e32 v138, s29, v191
	ds_read_b128 v[196:199], v138
	ds_read_b128 v[200:203], v138 offset:1024
	ds_read_b128 v[204:207], v138 offset:2048
	ds_read_b128 v[208:211], v138 offset:3072
	s_add_u32 s24, s36, 0x40000
	s_addc_u32 s25, s37, 0
	s_mov_b32 m0, s63
	v_lshl_add_u64 v[182:183], s[24:25], 0, v[148:149]
	ds_read_b128 v[212:215], v194 offset:32768
	ds_read_b128 v[216:219], v194 offset:33792
	ds_read_b128 v[220:223], v194 offset:34816
	ds_read_b128 v[224:227], v194 offset:35840
	ds_read_b128 v[228:231], v194 offset:36864
	ds_read_b128 v[232:235], v194 offset:37888
	ds_read_b128 v[236:239], v194 offset:38912
	ds_read_b128 v[240:243], v194 offset:39936
	global_load_lds_dwordx4 v[182:183], off
	v_lshl_add_u64 v[182:183], s[24:25], 0, v[144:145]
	s_mov_b32 m0, s64
	s_nop 0
	global_load_lds_dwordx4 v[182:183], off
	s_waitcnt vmcnt(8)
	s_waitcnt lgkmcnt(0)
	s_barrier
	s_setprio 1
	s_waitcnt lgkmcnt(0)
	v_mfma_f32_16x16x32_bf16 v[126:129], v[130:133], v[212:215], v[126:129]
	v_mfma_f32_16x16x32_bf16 v[122:125], v[158:161], v[212:215], v[122:125]
	v_mfma_f32_16x16x32_bf16 v[110:113], v[130:133], v[220:223], v[110:113]
	v_mfma_f32_16x16x32_bf16 v[106:109], v[158:161], v[220:223], v[106:109]
	v_mfma_f32_16x16x32_bf16 v[94:97], v[130:133], v[228:231], v[94:97]
	v_mfma_f32_16x16x32_bf16 v[90:93], v[158:161], v[228:231], v[90:93]
	v_mfma_f32_16x16x32_bf16 v[78:81], v[130:133], v[236:239], v[78:81]
	v_mfma_f32_16x16x32_bf16 v[74:77], v[158:161], v[236:239], v[74:77]
	v_mfma_f32_16x16x32_bf16 v[126:129], v[134:137], v[216:219], v[126:129]
	v_mfma_f32_16x16x32_bf16 v[122:125], v[162:165], v[216:219], v[122:125]
	v_mfma_f32_16x16x32_bf16 v[110:113], v[134:137], v[224:227], v[110:113]
	v_mfma_f32_16x16x32_bf16 v[106:109], v[162:165], v[224:227], v[106:109]
	v_mfma_f32_16x16x32_bf16 v[94:97], v[134:137], v[232:235], v[94:97]
	v_mfma_f32_16x16x32_bf16 v[90:93], v[162:165], v[232:235], v[90:93]
	v_mfma_f32_16x16x32_bf16 v[78:81], v[134:137], v[240:243], v[78:81]
	v_mfma_f32_16x16x32_bf16 v[74:77], v[162:165], v[240:243], v[74:77]
	s_setprio 0
	s_setprio 1
	v_mfma_f32_16x16x32_bf16 v[118:121], v[196:199], v[212:215], v[118:121]
	v_mfma_f32_16x16x32_bf16 v[114:117], v[204:207], v[212:215], v[114:117]
	v_mfma_f32_16x16x32_bf16 v[102:105], v[196:199], v[220:223], v[102:105]
	v_mfma_f32_16x16x32_bf16 v[98:101], v[204:207], v[220:223], v[98:101]
	v_mfma_f32_16x16x32_bf16 v[86:89], v[196:199], v[228:231], v[86:89]
	v_mfma_f32_16x16x32_bf16 v[82:85], v[204:207], v[228:231], v[82:85]
	v_mfma_f32_16x16x32_bf16 v[70:73], v[196:199], v[236:239], v[70:73]
	v_mfma_f32_16x16x32_bf16 v[66:69], v[204:207], v[236:239], v[66:69]
	v_mfma_f32_16x16x32_bf16 v[118:121], v[200:203], v[216:219], v[118:121]
	v_mfma_f32_16x16x32_bf16 v[114:117], v[208:211], v[216:219], v[114:117]
	v_mfma_f32_16x16x32_bf16 v[102:105], v[200:203], v[224:227], v[102:105]
	v_mfma_f32_16x16x32_bf16 v[98:101], v[208:211], v[224:227], v[98:101]
	v_mfma_f32_16x16x32_bf16 v[86:89], v[200:203], v[232:235], v[86:89]
	v_mfma_f32_16x16x32_bf16 v[82:85], v[208:211], v[232:235], v[82:85]
	v_mfma_f32_16x16x32_bf16 v[70:73], v[200:203], v[240:243], v[70:73]
	v_mfma_f32_16x16x32_bf16 v[66:69], v[208:211], v[240:243], v[66:69]
	s_setprio 0
	s_barrier
	s_add_i32 s24, s28, s60
	v_lshl_add_u64 v[166:167], v[166:167], 0, s[14:15]
	s_mov_b32 m0, s24
	ds_read_b128 v[212:215], v194 offset:49152
	ds_read_b128 v[216:219], v194 offset:50176
	ds_read_b128 v[220:223], v194 offset:51200
	ds_read_b128 v[224:227], v194 offset:52224
	ds_read_b128 v[228:231], v194 offset:53248
	ds_read_b128 v[232:235], v194 offset:54272
	ds_read_b128 v[236:239], v194 offset:55296
	ds_read_b128 v[240:243], v194 offset:56320
	global_load_lds_dwordx4 v[166:167], off
	s_add_i32 m0, s24, 0x2000
	s_add_u32 s4, s4, 0x40080
	v_lshl_add_u64 v[166:167], v[244:245], 0, s[14:15]
	s_addc_u32 s5, s5, 0
	s_add_i32 s24, s29, s60
	global_load_lds_dwordx4 v[166:167], off
	v_lshl_add_u64 v[166:167], s[4:5], 0, v[146:147]
	s_mov_b32 m0, s24
	s_nop 0
	global_load_lds_dwordx4 v[166:167], off
	v_lshl_add_u64 v[166:167], s[4:5], 0, v[142:143]
	s_add_i32 m0, s24, 0x2000
	s_nop 0
	global_load_lds_dwordx4 v[166:167], off
	v_lshl_add_u64 v[166:167], v[246:247], 0, s[14:15]
	s_mov_b32 m0, s65
	s_nop 0
	global_load_lds_dwordx4 v[166:167], off
	v_lshl_add_u64 v[166:167], v[248:249], 0, s[14:15]
	s_mov_b32 m0, s70
	s_nop 0
	global_load_lds_dwordx4 v[166:167], off
	s_waitcnt vmcnt(8)
	s_waitcnt lgkmcnt(0)
	s_barrier
	s_setprio 1
	s_waitcnt lgkmcnt(0)
	v_mfma_f32_16x16x32_bf16 v[60:63], v[130:133], v[212:215], v[60:63]
	v_mfma_f32_16x16x32_bf16 v[56:59], v[158:161], v[212:215], v[56:59]
	v_mfma_f32_16x16x32_bf16 v[44:47], v[130:133], v[220:223], v[44:47]
	v_mfma_f32_16x16x32_bf16 v[40:43], v[158:161], v[220:223], v[40:43]
	v_mfma_f32_16x16x32_bf16 v[28:31], v[130:133], v[228:231], v[28:31]
	v_mfma_f32_16x16x32_bf16 v[24:27], v[158:161], v[228:231], v[24:27]
	v_mfma_f32_16x16x32_bf16 v[12:15], v[130:133], v[236:239], v[12:15]
	v_mfma_f32_16x16x32_bf16 v[8:11], v[158:161], v[236:239], v[8:11]
	v_mfma_f32_16x16x32_bf16 v[60:63], v[134:137], v[216:219], v[60:63]
	v_mfma_f32_16x16x32_bf16 v[56:59], v[162:165], v[216:219], v[56:59]
	v_mfma_f32_16x16x32_bf16 v[44:47], v[134:137], v[224:227], v[44:47]
	v_mfma_f32_16x16x32_bf16 v[40:43], v[162:165], v[224:227], v[40:43]
	v_mfma_f32_16x16x32_bf16 v[28:31], v[134:137], v[232:235], v[28:31]
	v_mfma_f32_16x16x32_bf16 v[24:27], v[162:165], v[232:235], v[24:27]
	v_mfma_f32_16x16x32_bf16 v[12:15], v[134:137], v[240:243], v[12:15]
	v_mfma_f32_16x16x32_bf16 v[8:11], v[162:165], v[240:243], v[8:11]
	s_setprio 0
	s_setprio 1
	v_mfma_f32_16x16x32_bf16 v[52:55], v[196:199], v[212:215], v[52:55]
	v_mfma_f32_16x16x32_bf16 v[48:51], v[204:207], v[212:215], v[48:51]
	v_mfma_f32_16x16x32_bf16 v[36:39], v[196:199], v[220:223], v[36:39]
	v_mfma_f32_16x16x32_bf16 v[32:35], v[204:207], v[220:223], v[32:35]
	v_mfma_f32_16x16x32_bf16 v[20:23], v[196:199], v[228:231], v[20:23]
	v_mfma_f32_16x16x32_bf16 v[16:19], v[204:207], v[228:231], v[16:19]
	v_mfma_f32_16x16x32_bf16 v[4:7], v[196:199], v[236:239], v[4:7]
	v_mfma_f32_16x16x32_bf16 v[0:3], v[204:207], v[236:239], v[0:3]
	v_mfma_f32_16x16x32_bf16 v[52:55], v[200:203], v[216:219], v[52:55]
	v_mfma_f32_16x16x32_bf16 v[48:51], v[208:211], v[216:219], v[48:51]
	v_mfma_f32_16x16x32_bf16 v[36:39], v[200:203], v[224:227], v[36:39]
	v_mfma_f32_16x16x32_bf16 v[32:35], v[208:211], v[224:227], v[32:35]
	v_mfma_f32_16x16x32_bf16 v[20:23], v[200:203], v[232:235], v[20:23]
	v_mfma_f32_16x16x32_bf16 v[16:19], v[208:211], v[232:235], v[16:19]
	v_mfma_f32_16x16x32_bf16 v[4:7], v[200:203], v[240:243], v[4:7]
	v_mfma_f32_16x16x32_bf16 v[0:3], v[208:211], v[240:243], v[0:3]
	s_setprio 0
	s_barrier
	s_add_i32 s21, s21, 2
	s_add_u32 s0, s0, 0x100
	s_addc_u32 s1, s1, 0
	s_add_u32 s19, s19, 0x100
	s_addc_u32 s20, s20, 0
	s_cmp_gt_u32 s21, 13
	s_cbranch_scc0 .LBB0_581
	s_and_b64 vcc, exec, s[40:41]
	s_cbranch_vccz .LBB0_584
	s_barrier

.Lepi_done:
	s_mov_b32 s101, 1
	s_cbranch_vccnz .LBB0_577
	s_andn2_b64 vcc, exec, s[66:67]
	s_cbranch_vccnz .LBB0_576
	s_barrier
	s_branch .LBB0_576
